# MLA attention tile loop: K fragment LDS reads issued right after the tile barrier (before the next-tile prefetch block and the row guards)
# speedup vs baseline: 1.0020x; 1.0020x over previous
; template <int DK, bool BIAS> ...
;     ...
;   auto kload = [&](int kg, int chn) -> uint4 {
;     uint4 u = make_uint4(0, 0, 0, 0);
;     if (kg < T) { if (DK == 64 || chn < 8) u = *(const uint4*)(Kp + (size_t)(rowb + kg) * ldk + chn * 8); else u = *(const uint4*)(K2p + (size_t)(rowb + kg) * ldk2 + (chn - 8) * 8); }
;     return u; };
;   auto prefetch = [&](int j, uint4& rk0, uint4& rk1, uint4& rv, float& rfk) {
;     rk0 = kload(64 * j + krow0, kch0);
;     if (NPIECE > 512 && tid + 512 < NPIECE) rk1 = kload(64 * j + krow1, kch1);
;     { const int kg = 64 * j + vrow; rv = make_uint4(0, 0, 0, 0); if (kg < T) rv = *(const uint4*)(Vp + (size_t)(rowb + kg) * ldv + vch * 8); }
;     if (BIAS && tid < 64) { const int kg = 64 * j + tid; rfk = kg < T ? -fc[kg] * LOG2E : 0.f; }
;     ...
;         for (int kt = 0; kt < 4; ++kt) { const bf16x8 ak = *(const bf16x8*)(Ksm + (buf * 64 + 16 * kt + fr) * KST + 32 * ks + 8 * fq);
.LBB0_1852:
	ds_read_b128 v[80:83], v202
	ds_read_b128 v[156:159], v202 offset:64
	ds_read_b128 v[88:91], v202 offset:3328
	ds_read_b128 v[96:99], v202 offset:6656
	ds_read_b128 v[104:107], v202 offset:9984
	ds_read_b128 v[210:213], v202 offset:3392
	ds_read_b128 v[214:217], v202 offset:6720
	ds_read_b128 v[218:221], v202 offset:10048
	ds_read_b128 v[222:225], v202 offset:128
	ds_read_b128 v[226:229], v202 offset:3456
	ds_read_b128 v[230:233], v202 offset:10112
	ds_read_b128 v[234:237], v202 offset:6784
	s_add_i32 s42, s43, -3
	s_cmp_lt_u32 s42, s21
	s_cselect_b64 s[16:17], -1, 0
	s_cmp_ge_u32 s42, s21
	s_cbranch_scc1 .LBB0_1862
	s_add_i32 s0, s58, 0xbf
	s_cmp_lt_i32 s0, s29
	s_cbranch_scc0 .Lpf_mla1_slow
	s_waitcnt vmcnt(0)
	v_mov_b32_e32 v131, v130
	v_add_u32_e32 v24, s58, v116
	v_add_u32_e32 v24, 0x80, v24
	v_ashrrev_i32_e32 v25, 31, v24
	v_lshlrev_b64 v[26:27], 11, v[24:25]
	v_lshlrev_b64 v[24:25], 6, v[24:25]
	v_lshl_add_u64 v[24:25], v[124:125], 0, v[24:25]
	v_lshl_add_u64 v[26:27], v[122:123], 0, v[26:27]
	v_lshl_add_u64 v[24:25], v[24:25], 0, s[48:49]
	v_cndmask_b32_e64 v25, v25, v27, s[10:11]
	v_cndmask_b32_e64 v24, v24, v26, s[10:11]
	global_load_dwordx4 v[24:27], v[24:25], off
	s_and_saveexec_b64 s[0:1], s[6:7]
	s_cbranch_execz .Lpf_mla1_e
	v_add_u32_e32 v28, s58, v118
	v_add_u32_e32 v28, 0x80, v28
	v_ashrrev_i32_e32 v29, 31, v28
	v_lshlrev_b64 v[28:29], v152, v[28:29]
	v_lshl_add_u64 v[28:29], v[150:151], 0, v[28:29]
	global_load_dwordx4 v[28:31], v[28:29], off

; #define MFMA(a, b, c) __builtin_amdgcn_mfma_f32_16x16x32_bf16((a), (b), (c), 0, 0, 0)
; template <int DK, bool BIAS> ...
;     ...
;       for (int ks = 0; ks < KS; ++ks)
; #pragma unroll
;         for (int kt = 0; kt < 4; ++kt) { const bf16x8 ak = *(const bf16x8*)(Ksm + (buf * 64 + 16 * kt + fr) * KST + 32 * ks + 8 * fq);
; #pragma unroll
;           for (int qi = 0; qi < 2; ++qi) S[kt][qi] = MFMA(ak, qf[qi][ks], S[kt][qi]); }
;       bf16x8 pf[2][2];
;       if (64 * j + 63 > q0 + 32 * w) {
; #pragma unroll
;         for (int qi = 0; qi < 2; ++qi) { const int qg = q0 + 32 * w + 16 * qi + fr;
; #pragma unroll
;           for (int kt = 0; kt < 4; ++kt)
; #pragma unroll
;             for (int r = 0; r < 4; ++r) { const int kg = 64 * j + 16 * kt + 4 * fq + r; if (kg > qg) S[kt][qi][r] = -1e30f; } }
;       }
.LBB0_1862:
	s_and_saveexec_b64 s[0:1], s[8:9]
	s_cbranch_execz .LBB0_1868
	v_cmp_le_i32_e32 vcc, s58, v201
	s_and_saveexec_b64 s[94:95], vcc
	s_cbranch_execz .LBB0_1867
	s_add_i32 s18, s58, 63
	v_cmp_gt_i32_e32 vcc, s18, v153
	s_waitcnt lgkmcnt(11)
	v_mfma_f32_16x16x32_bf16 v[84:87], v[80:83], v[4:7], 0
	v_mfma_f32_16x16x32_bf16 v[80:83], v[80:83], v[8:11], 0
	s_waitcnt lgkmcnt(10)
	v_mfma_f32_16x16x32_bf16 v[84:87], v[156:159], v[0:3], v[84:87]
	v_mfma_f32_16x16x32_bf16 v[80:83], v[156:159], v[20:23], v[80:83]
	s_waitcnt lgkmcnt(9)
	v_mfma_f32_16x16x32_bf16 v[92:95], v[88:91], v[4:7], 0
	v_mfma_f32_16x16x32_bf16 v[88:91], v[88:91], v[8:11], 0
	s_waitcnt lgkmcnt(6)
	v_mfma_f32_16x16x32_bf16 v[92:95], v[210:213], v[0:3], v[92:95]
	v_mfma_f32_16x16x32_bf16 v[156:159], v[210:213], v[20:23], v[88:91]
	v_mfma_f32_16x16x32_bf16 v[100:103], v[96:99], v[4:7], 0
	v_mfma_f32_16x16x32_bf16 v[96:99], v[96:99], v[8:11], 0
	s_waitcnt lgkmcnt(5)
	v_mfma_f32_16x16x32_bf16 v[160:163], v[214:217], v[0:3], v[100:103]
	v_mfma_f32_16x16x32_bf16 v[164:167], v[214:217], v[20:23], v[96:99]
	v_mfma_f32_16x16x32_bf16 v[108:111], v[104:107], v[4:7], 0
	v_mfma_f32_16x16x32_bf16 v[104:107], v[104:107], v[8:11], 0
	s_waitcnt lgkmcnt(4)
	v_mfma_f32_16x16x32_bf16 v[108:111], v[218:221], v[0:3], v[108:111]
	v_mfma_f32_16x16x32_bf16 v[168:171], v[218:221], v[20:23], v[104:107]
	s_waitcnt lgkmcnt(3)
	v_mfma_f32_16x16x32_bf16 v[100:103], v[222:225], v[12:15], v[84:87]
	v_mfma_f32_16x16x32_bf16 v[88:91], v[222:225], v[16:19], v[80:83]
	s_waitcnt lgkmcnt(2)
	v_mfma_f32_16x16x32_bf16 v[96:99], v[226:229], v[12:15], v[92:95]
	v_mfma_f32_16x16x32_bf16 v[84:87], v[226:229], v[16:19], v[156:159]
	s_waitcnt lgkmcnt(0)
	v_mfma_f32_16x16x32_bf16 v[104:107], v[234:237], v[12:15], v[160:163]
	v_mfma_f32_16x16x32_bf16 v[80:83], v[234:237], v[16:19], v[164:167]
	v_mfma_f32_16x16x32_bf16 v[108:111], v[230:233], v[12:15], v[108:111]
	v_mfma_f32_16x16x32_bf16 v[92:95], v[230:233], v[16:19], v[168:171]
	s_and_saveexec_b64 s[18:19], vcc
	s_cbranch_execz .LBB0_1866
	v_add_u32_e32 v131, s58, v200
	v_mov_b32_e32 v156, s30
	v_cmp_gt_i32_e32 vcc, v131, v194
	v_add_u32_e32 v157, 3, v131
	v_add_u32_e32 v158, 16, v131
	v_cndmask_b32_e32 v155, v100, v156, vcc
	v_cmp_lt_i32_e32 vcc, v131, v194
	v_add_u32_e32 v159, 17, v131
	v_add_u32_e32 v160, 18, v131
	v_cndmask_b32_e32 v100, v155, v100, vcc
	v_add_u32_e32 v155, 2, v131
	v_cndmask_b32_e32 v101, v193, v101, vcc
	v_cmp_le_i32_e32 vcc, v155, v194
	v_add_u32_e32 v161, 19, v131
	v_add_u32_e32 v162, 32, v131
	v_cndmask_b32_e32 v102, v193, v102, vcc
	v_cmp_le_i32_e32 vcc, v157, v194
	v_add_u32_e32 v163, 33, v131
	v_add_u32_e32 v164, 34, v131
	v_cndmask_b32_e32 v103, v193, v103, vcc
	v_cmp_gt_i32_e32 vcc, v158, v194
	v_add_u32_e32 v165, 35, v131
	v_add_u32_e32 v166, 48, v131
	v_cndmask_b32_e32 v96, v96, v156, vcc
	v_cmp_le_i32_e32 vcc, v159, v194
	v_add_u32_e32 v167, 49, v131
	v_add_u32_e32 v168, 50, v131
	v_cndmask_b32_e32 v97, v193, v97, vcc
	v_cmp_le_i32_e32 vcc, v160, v194
	v_add_u32_e32 v169, 51, v131
	s_nop 0
	v_cndmask_b32_e32 v98, v193, v98, vcc
	v_cmp_le_i32_e32 vcc, v161, v194
	v_cmp_gt_i32_e64 s[100:101], v162, v194
	s_nop 0
	v_cndmask_b32_e32 v99, v193, v99, vcc
	v_cndmask_b32_e64 v104, v104, v156, s[100:101]
	v_cmp_le_i32_e32 vcc, v163, v194
	v_cmp_le_i32_e64 s[100:101], v164, v194
	s_nop 0
	v_cndmask_b32_e32 v105, v193, v105, vcc
	v_cndmask_b32_e64 v106, v193, v106, s[100:101]
	v_cmp_le_i32_e32 vcc, v165, v194
	v_cmp_gt_i32_e64 s[100:101], v166, v194
	s_nop 0
	v_cndmask_b32_e32 v107, v193, v107, vcc
	v_cndmask_b32_e64 v108, v108, v156, s[100:101]
	v_cmp_le_i32_e32 vcc, v167, v194
	v_cmp_le_i32_e64 s[100:101], v168, v194
	s_nop 0
	v_cndmask_b32_e32 v109, v193, v109, vcc
	v_cndmask_b32_e64 v110, v193, v110, s[100:101]
	v_cmp_le_i32_e32 vcc, v169, v194
	v_cmp_gt_i32_e64 s[100:101], v131, v195
	s_nop 0
	v_cndmask_b32_e32 v111, v193, v111, vcc
	v_cndmask_b32_e64 v156, v88, v156, s[100:101]
	v_cmp_lt_i32_e32 vcc, v131, v195
	s_nop 1
	v_cndmask_b32_e32 v88, v156, v88, vcc
	v_cndmask_b32_e32 v89, v193, v89, vcc
	v_cmp_le_i32_e32 vcc, v155, v195
	v_mov_b32_e32 v156, s30
	s_nop 0
	v_cndmask_b32_e32 v90, v193, v90, vcc
	v_cmp_le_i32_e32 vcc, v157, v195
	v_cmp_gt_i32_e64 s[100:101], v158, v195
	s_nop 0
	v_cndmask_b32_e32 v91, v193, v91, vcc
	v_cndmask_b32_e64 v84, v84, v156, s[100:101]
	v_cmp_le_i32_e32 vcc, v159, v195
	v_cmp_le_i32_e64 s[100:101], v160, v195
	s_nop 0
	v_cndmask_b32_e32 v85, v193, v85, vcc
	v_cndmask_b32_e64 v86, v193, v86, s[100:101]
	v_cmp_le_i32_e32 vcc, v161, v195
	v_cmp_gt_i32_e64 s[100:101], v162, v195
	s_nop 0
	v_cndmask_b32_e32 v87, v193, v87, vcc
	v_cndmask_b32_e64 v80, v80, v156, s[100:101]
	v_cmp_le_i32_e32 vcc, v163, v195
	v_cmp_le_i32_e64 s[100:101], v164, v195
	s_nop 0
	v_cndmask_b32_e32 v81, v193, v81, vcc
	v_cndmask_b32_e64 v82, v193, v82, s[100:101]
	v_cmp_le_i32_e32 vcc, v165, v195
	v_cmp_gt_i32_e64 s[100:101], v166, v195
	s_nop 0
	v_cndmask_b32_e32 v83, v193, v83, vcc
	v_cndmask_b32_e64 v92, v92, v156, s[100:101]
	v_cmp_le_i32_e32 vcc, v167, v195
	v_cmp_le_i32_e64 s[100:101], v168, v195
	s_nop 0
	v_cndmask_b32_e32 v93, v193, v93, vcc
	v_cndmask_b32_e64 v94, v193, v94, s[100:101]
	v_cmp_le_i32_e32 vcc, v169, v195
	s_nop 1
	v_cndmask_b32_e32 v95, v193, v95, vcc

; template <int DK, bool BIAS> ...
;     ...
;   auto kload = [&](int kg, int chn) -> uint4 {
;     uint4 u = make_uint4(0, 0, 0, 0);
;     if (kg < T) { if (DK == 64 || chn < 8) u = *(const uint4*)(Kp + (size_t)(rowb + kg) * ldk + chn * 8); else u = *(const uint4*)(K2p + (size_t)(rowb + kg) * ldk2 + (chn - 8) * 8); }
;     return u; };
;   auto prefetch = [&](int j, uint4& rk0, uint4& rk1, uint4& rv, float& rfk) {
;     rk0 = kload(64 * j + krow0, kch0);
;     if (NPIECE > 512 && tid + 512 < NPIECE) rk1 = kload(64 * j + krow1, kch1);
;     { const int kg = 64 * j + vrow; rv = make_uint4(0, 0, 0, 0); if (kg < T) rv = *(const uint4*)(Vp + (size_t)(rowb + kg) * ldv + vch * 8); }
;     if (BIAS && tid < 64) { const int kg = 64 * j + tid; rfk = kg < T ? -fc[kg] * LOG2E : 0.f; }
;     ...
;         for (int kt = 0; kt < 4; ++kt) { const bf16x8 ak = *(const bf16x8*)(Ksm + (buf * 64 + 16 * kt + fr) * KST + 32 * ks + 8 * fq);
.LBB0_1872:
	s_waitcnt lgkmcnt(0)
	s_barrier
	s_and_b64 vcc, exec, s[0:1]
	s_cbranch_vccnz .LBB0_1851
	ds_read_b128 v[80:83], v205
	ds_read_b128 v[156:159], v205 offset:64
	ds_read_b128 v[88:91], v205 offset:3328
	ds_read_b128 v[96:99], v205 offset:6656
	ds_read_b128 v[104:107], v205 offset:9984
	ds_read_b128 v[210:213], v205 offset:3392
	ds_read_b128 v[214:217], v205 offset:6720
	ds_read_b128 v[218:221], v205 offset:10048
	ds_read_b128 v[222:225], v205 offset:128
	ds_read_b128 v[226:229], v205 offset:6784
	ds_read_b128 v[230:233], v205 offset:3456
	ds_read_b128 v[234:237], v205 offset:10112
	s_cmp_gt_u32 s43, s21
	s_cbranch_scc1 .LBB0_1884
	s_add_i32 s0, s58, 0xff
	s_cmp_lt_i32 s0, s29
	s_cbranch_scc0 .Lpf_mla2_slow
	s_waitcnt vmcnt(0)
	v_mov_b32_e32 v131, v130
	v_add_u32_e32 v36, s58, v116
	v_add_u32_e32 v36, 0xc0, v36
	v_ashrrev_i32_e32 v37, 31, v36
	v_lshlrev_b64 v[38:39], 11, v[36:37]
	v_lshlrev_b64 v[36:37], 6, v[36:37]
	v_lshl_add_u64 v[36:37], v[124:125], 0, v[36:37]
	v_lshl_add_u64 v[38:39], v[122:123], 0, v[38:39]
	v_lshl_add_u64 v[36:37], v[36:37], 0, s[48:49]
	v_cndmask_b32_e64 v37, v37, v39, s[10:11]
	v_cndmask_b32_e64 v36, v36, v38, s[10:11]
	global_load_dwordx4 v[36:39], v[36:37], off
	s_and_saveexec_b64 s[0:1], s[6:7]
	s_cbranch_execz .Lpf_mla2_e
	v_add_u32_e32 v40, s58, v118
	v_add_u32_e32 v40, 0xc0, v40
	v_ashrrev_i32_e32 v41, 31, v40
	v_lshlrev_b64 v[40:41], v152, v[40:41]
	v_lshl_add_u64 v[40:41], v[150:151], 0, v[40:41]
	global_load_dwordx4 v[40:43], v[40:41], off

; #define MFMA(a, b, c) __builtin_amdgcn_mfma_f32_16x16x32_bf16((a), (b), (c), 0, 0, 0)
; template <int DK, bool BIAS> ...
;     ...
;       for (int ks = 0; ks < KS; ++ks)
; #pragma unroll
;         for (int kt = 0; kt < 4; ++kt) { const bf16x8 ak = *(const bf16x8*)(Ksm + (buf * 64 + 16 * kt + fr) * KST + 32 * ks + 8 * fq);
; #pragma unroll
;           for (int qi = 0; qi < 2; ++qi) S[kt][qi] = MFMA(ak, qf[qi][ks], S[kt][qi]); }
;       bf16x8 pf[2][2];
;       if (64 * j + 63 > q0 + 32 * w) {
; #pragma unroll
;         for (int qi = 0; qi < 2; ++qi) { const int qg = q0 + 32 * w + 16 * qi + fr;
; #pragma unroll
;           for (int kt = 0; kt < 4; ++kt)
; #pragma unroll
;             for (int r = 0; r < 4; ++r) { const int kg = 64 * j + 16 * kt + 4 * fq + r; if (kg > qg) S[kt][qi][r] = -1e30f; } }
;       }
.LBB0_1885:
	s_add_i32 s16, s58, 64
	v_cmp_le_i32_e32 vcc, s16, v201
	s_and_saveexec_b64 s[16:17], vcc
	s_cbranch_execz .LBB0_1889
	s_add_i32 s18, s58, 0x7f
	v_cmp_gt_i32_e32 vcc, s18, v153
	s_waitcnt lgkmcnt(11)
	v_mfma_f32_16x16x32_bf16 v[84:87], v[80:83], v[4:7], 0
	v_mfma_f32_16x16x32_bf16 v[80:83], v[80:83], v[8:11], 0
	s_waitcnt lgkmcnt(10)
	v_mfma_f32_16x16x32_bf16 v[84:87], v[156:159], v[0:3], v[84:87]
	v_mfma_f32_16x16x32_bf16 v[80:83], v[156:159], v[20:23], v[80:83]
	s_waitcnt lgkmcnt(9)
	v_mfma_f32_16x16x32_bf16 v[92:95], v[88:91], v[4:7], 0
	v_mfma_f32_16x16x32_bf16 v[88:91], v[88:91], v[8:11], 0
	s_waitcnt lgkmcnt(6)
	v_mfma_f32_16x16x32_bf16 v[92:95], v[210:213], v[0:3], v[92:95]
	v_mfma_f32_16x16x32_bf16 v[156:159], v[210:213], v[20:23], v[88:91]
	v_mfma_f32_16x16x32_bf16 v[100:103], v[96:99], v[4:7], 0
	v_mfma_f32_16x16x32_bf16 v[96:99], v[96:99], v[8:11], 0
	s_waitcnt lgkmcnt(5)
	v_mfma_f32_16x16x32_bf16 v[160:163], v[214:217], v[0:3], v[100:103]
	v_mfma_f32_16x16x32_bf16 v[164:167], v[214:217], v[20:23], v[96:99]
	v_mfma_f32_16x16x32_bf16 v[108:111], v[104:107], v[4:7], 0
	v_mfma_f32_16x16x32_bf16 v[104:107], v[104:107], v[8:11], 0
	s_waitcnt lgkmcnt(4)
	v_mfma_f32_16x16x32_bf16 v[108:111], v[218:221], v[0:3], v[108:111]
	v_mfma_f32_16x16x32_bf16 v[168:171], v[218:221], v[20:23], v[104:107]
	s_waitcnt lgkmcnt(3)
	v_mfma_f32_16x16x32_bf16 v[100:103], v[222:225], v[12:15], v[84:87]
	v_mfma_f32_16x16x32_bf16 v[88:91], v[222:225], v[16:19], v[80:83]
	s_waitcnt lgkmcnt(1)
	v_mfma_f32_16x16x32_bf16 v[96:99], v[230:233], v[12:15], v[92:95]
	v_mfma_f32_16x16x32_bf16 v[80:83], v[230:233], v[16:19], v[156:159]
	v_mfma_f32_16x16x32_bf16 v[104:107], v[226:229], v[12:15], v[160:163]
	v_mfma_f32_16x16x32_bf16 v[84:87], v[226:229], v[16:19], v[164:167]
	s_waitcnt lgkmcnt(0)
	v_mfma_f32_16x16x32_bf16 v[108:111], v[234:237], v[12:15], v[108:111]
	v_mfma_f32_16x16x32_bf16 v[92:95], v[234:237], v[16:19], v[168:171]
	s_and_saveexec_b64 s[18:19], vcc
	s_cbranch_execz .LBB0_1888
	v_add_u32_e32 v131, s58, v200
	v_add_u32_e32 v155, 64, v131
	v_mov_b32_e32 v156, s30
	v_cmp_gt_i32_e32 vcc, v155, v194
	v_add_u32_e32 v157, 0x42, v131
	v_add_u32_e32 v158, 0x43, v131
	v_cndmask_b32_e32 v156, v100, v156, vcc
	v_cmp_lt_i32_e32 vcc, v155, v194
	v_add_u32_e32 v159, 0x50, v131
	v_add_u32_e32 v160, 0x51, v131
	v_cndmask_b32_e32 v100, v156, v100, vcc
	v_cndmask_b32_e32 v101, v193, v101, vcc
	v_cmp_le_i32_e32 vcc, v157, v194
	v_mov_b32_e32 v156, s30
	v_add_u32_e32 v161, 0x52, v131
	v_cndmask_b32_e32 v102, v193, v102, vcc
	v_cmp_le_i32_e32 vcc, v158, v194
	v_add_u32_e32 v162, 0x53, v131
	v_add_u32_e32 v163, 0x60, v131
	v_cndmask_b32_e32 v103, v193, v103, vcc
	v_cmp_gt_i32_e32 vcc, v159, v194
	v_add_u32_e32 v164, 0x61, v131
	v_add_u32_e32 v165, 0x62, v131
	v_cndmask_b32_e32 v96, v96, v156, vcc
	v_cmp_le_i32_e32 vcc, v160, v194
	v_add_u32_e32 v166, 0x63, v131
	v_add_u32_e32 v167, 0x70, v131
	v_cndmask_b32_e32 v97, v193, v97, vcc
	v_cmp_le_i32_e32 vcc, v161, v194
	v_add_u32_e32 v168, 0x71, v131
	v_add_u32_e32 v169, 0x72, v131
	v_cndmask_b32_e32 v98, v193, v98, vcc
	v_cmp_le_i32_e32 vcc, v162, v194
	v_add_u32_e32 v131, 0x73, v131
	s_nop 0
	v_cndmask_b32_e32 v99, v193, v99, vcc
	v_cmp_gt_i32_e32 vcc, v163, v194
	v_cmp_le_i32_e64 s[100:101], v164, v194
	s_nop 0
	v_cndmask_b32_e32 v104, v104, v156, vcc
	v_cndmask_b32_e64 v105, v193, v105, s[100:101]
	v_cmp_le_i32_e32 vcc, v165, v194
	v_cmp_le_i32_e64 s[100:101], v166, v194
	s_nop 0
	v_cndmask_b32_e32 v106, v193, v106, vcc
	v_cndmask_b32_e64 v107, v193, v107, s[100:101]
	v_cmp_gt_i32_e32 vcc, v167, v194
	v_cmp_le_i32_e64 s[100:101], v168, v194
	s_nop 0
	v_cndmask_b32_e32 v108, v108, v156, vcc
	v_cndmask_b32_e64 v109, v193, v109, s[100:101]
	v_cmp_le_i32_e32 vcc, v169, v194
	v_cmp_le_i32_e64 s[100:101], v131, v194
	s_nop 0
	v_cndmask_b32_e32 v110, v193, v110, vcc
	v_cndmask_b32_e64 v111, v193, v111, s[100:101]
	v_cmp_gt_i32_e32 vcc, v155, v195
	s_nop 1
	v_cndmask_b32_e32 v156, v88, v156, vcc
	v_cmp_lt_i32_e32 vcc, v155, v195
	s_nop 1
	v_cndmask_b32_e32 v88, v156, v88, vcc
	v_cndmask_b32_e32 v89, v193, v89, vcc
	v_cmp_le_i32_e32 vcc, v157, v195
	v_mov_b32_e32 v156, s30
	s_nop 0
	v_cndmask_b32_e32 v90, v193, v90, vcc
	v_cmp_le_i32_e32 vcc, v158, v195
	v_cmp_gt_i32_e64 s[100:101], v159, v195
	s_nop 0
	v_cndmask_b32_e32 v91, v193, v91, vcc
	v_cndmask_b32_e64 v80, v80, v156, s[100:101]
	v_cmp_le_i32_e32 vcc, v160, v195
	v_cmp_le_i32_e64 s[100:101], v161, v195
	s_nop 0
	v_cndmask_b32_e32 v81, v193, v81, vcc
	v_cndmask_b32_e64 v82, v193, v82, s[100:101]
	v_cmp_le_i32_e32 vcc, v162, v195
	v_cmp_gt_i32_e64 s[100:101], v163, v195
	s_nop 0
	v_cndmask_b32_e32 v83, v193, v83, vcc
	v_cndmask_b32_e64 v84, v84, v156, s[100:101]
	v_cmp_le_i32_e32 vcc, v164, v195
	v_cmp_le_i32_e64 s[100:101], v165, v195
	s_nop 0
	v_cndmask_b32_e32 v85, v193, v85, vcc
	v_cndmask_b32_e64 v86, v193, v86, s[100:101]
	v_cmp_le_i32_e32 vcc, v166, v195
	v_cmp_gt_i32_e64 s[100:101], v167, v195
	s_nop 0
	v_cndmask_b32_e32 v87, v193, v87, vcc
	v_cndmask_b32_e64 v92, v92, v156, s[100:101]
	v_cmp_le_i32_e32 vcc, v168, v195
	v_cmp_le_i32_e64 s[100:101], v169, v195
	s_nop 0
	v_cndmask_b32_e32 v93, v193, v93, vcc
	v_cndmask_b32_e64 v94, v193, v94, s[100:101]
	v_cmp_le_i32_e32 vcc, v131, v195
	s_nop 1
	v_cndmask_b32_e32 v95, v193, v95, vcc
